# phase B cache K/V conversion loops: all 8 items' loads issued up front (batched); phase 0 xconv row loads de-serialised
# speedup vs baseline: 1.0103x; 1.0103x over previous
; DI int tidx() { int t = __builtin_amdgcn_workitem_id_x(); asm volatile("" : "+v"(t)); return t; }
; DI unsigned pk2(float lo, float hi) { unsigned r; asm("v_cvt_pk_bf16_f32 %0, %1, %2" : "=v"(r) : "v"(lo), "v"(hi)); return r; }
; DI void conv_cache_v(const P& p, int layer, int it) {
;   const int kg = it & 127, h = (it >> 7) & 7, b = it >> 10;
;   const int d = tidx() & 63, ko = tidx() >> 6;
;   const int key0 = kg * 32 + ko * 8;
;   const float* s = p.cache_v + (size_t)layer * 8 * 4096 * 512 + ((size_t)(b * 4096 + key0) * 8 + h) * 64 + d;
;   float v[8];
; #pragma unroll
;   for (int e = 0; e < 8; ++e) v[e] = __builtin_nontemporal_load(s + (size_t)e * 512);
;   bf16_t* dst = (bf16_t*)(p.ws + W_VTS) + ((size_t)(b * 8 + h) * 64 + d) * LS + (key0 & ~15) + ((key0 & 8) >> 1);
;   *(u32x2*)dst = u32x2{pk2(v[0], v[1]), pk2(v[2], v[3])};
;   *(u32x2*)(dst + 8) = u32x2{pk2(v[4], v[5]), pk2(v[6], v[7])};
; }
; PHASE_FN void phaseB(const P& p, int layer, char* lds) {
;     ...
;       for (int k = 0; k < 8; ++k) conv_cache_v(p, layer, (mi - NPG - NCK) * 8 + k);
.LBB0_394:
	v_and_b32_e32 v0, 63, v158
	v_lshrrev_b32_e32 v2, 6, v158
	v_lshlrev_b32_e32 v3, 14, v2
	v_lshl_or_b32 v3, v0, 2, v3
	s_and_b32 s6, s22, 127
	s_lshl_b32 s6, s6, 5
	s_add_u32 s6, s6, s2
	s_lshl_b32 s6, s6, 11
	s_add_u32 s6, s0, s6
	s_addc_u32 s7, s1, 0
	global_load_dword v104, v3, s[6:7] nt
	global_load_dword v105, v3, s[6:7] offset:2048 nt
	s_add_u32 s6, s6, 0x1000
	s_addc_u32 s7, s7, 0
	global_load_dword v106, v3, s[6:7] nt
	global_load_dword v107, v3, s[6:7] offset:2048 nt
	s_add_u32 s6, s6, 0x1000
	s_addc_u32 s7, s7, 0
	global_load_dword v108, v3, s[6:7] nt
	global_load_dword v109, v3, s[6:7] offset:2048 nt
	s_add_u32 s6, s6, 0x1000
	s_addc_u32 s7, s7, 0
	global_load_dword v110, v3, s[6:7] nt
	global_load_dword v111, v3, s[6:7] offset:2048 nt
	s_add_u32 s6, s6, 0xd000
	s_addc_u32 s7, s7, 0
	global_load_dword v112, v3, s[6:7] nt
	global_load_dword v113, v3, s[6:7] offset:2048 nt
	s_add_u32 s6, s6, 0x1000
	s_addc_u32 s7, s7, 0
	global_load_dword v114, v3, s[6:7] nt
	global_load_dword v115, v3, s[6:7] offset:2048 nt
	s_add_u32 s6, s6, 0x1000
	s_addc_u32 s7, s7, 0
	global_load_dword v116, v3, s[6:7] nt
	global_load_dword v117, v3, s[6:7] offset:2048 nt
	s_add_u32 s6, s6, 0x1000
	s_addc_u32 s7, s7, 0
	global_load_dword v118, v3, s[6:7] nt
	global_load_dword v119, v3, s[6:7] offset:2048 nt
	s_add_u32 s6, s6, 0xd000
	s_addc_u32 s7, s7, 0
	global_load_dword v120, v3, s[6:7] nt
	global_load_dword v121, v3, s[6:7] offset:2048 nt
	s_add_u32 s6, s6, 0x1000
	s_addc_u32 s7, s7, 0
	global_load_dword v122, v3, s[6:7] nt
	global_load_dword v123, v3, s[6:7] offset:2048 nt
	s_add_u32 s6, s6, 0x1000
	s_addc_u32 s7, s7, 0
	global_load_dword v124, v3, s[6:7] nt
	global_load_dword v125, v3, s[6:7] offset:2048 nt
	s_add_u32 s6, s6, 0x1000
	s_addc_u32 s7, s7, 0
	global_load_dword v126, v3, s[6:7] nt
	global_load_dword v127, v3, s[6:7] offset:2048 nt
	s_add_u32 s6, s6, 0xd000
	s_addc_u32 s7, s7, 0
	global_load_dword v128, v3, s[6:7] nt
	global_load_dword v129, v3, s[6:7] offset:2048 nt
	s_add_u32 s6, s6, 0x1000
	s_addc_u32 s7, s7, 0
	global_load_dword v130, v3, s[6:7] nt
	global_load_dword v131, v3, s[6:7] offset:2048 nt
	s_add_u32 s6, s6, 0x1000
	s_addc_u32 s7, s7, 0
	global_load_dword v132, v3, s[6:7] nt
	global_load_dword v133, v3, s[6:7] offset:2048 nt
	s_add_u32 s6, s6, 0x1000
	s_addc_u32 s7, s7, 0
	global_load_dword v134, v3, s[6:7] nt
	global_load_dword v135, v3, s[6:7] offset:2048 nt
	s_add_u32 s6, s6, 0xd000
	s_addc_u32 s7, s7, 0
	global_load_dword v180, v3, s[6:7] nt
	global_load_dword v181, v3, s[6:7] offset:2048 nt
	s_add_u32 s6, s6, 0x1000
	s_addc_u32 s7, s7, 0
	global_load_dword v182, v3, s[6:7] nt
	global_load_dword v183, v3, s[6:7] offset:2048 nt
	s_add_u32 s6, s6, 0x1000
	s_addc_u32 s7, s7, 0
	global_load_dword v184, v3, s[6:7] nt
	global_load_dword v185, v3, s[6:7] offset:2048 nt
	s_add_u32 s6, s6, 0x1000
	s_addc_u32 s7, s7, 0
	global_load_dword v186, v3, s[6:7] nt
	global_load_dword v187, v3, s[6:7] offset:2048 nt
	s_add_u32 s6, s6, 0xd000
	s_addc_u32 s7, s7, 0
	global_load_dword v188, v3, s[6:7] nt
	global_load_dword v189, v3, s[6:7] offset:2048 nt
	s_add_u32 s6, s6, 0x1000
	s_addc_u32 s7, s7, 0
	global_load_dword v190, v3, s[6:7] nt
	global_load_dword v191, v3, s[6:7] offset:2048 nt
	s_add_u32 s6, s6, 0x1000
	s_addc_u32 s7, s7, 0
	global_load_dword v192, v3, s[6:7] nt
	global_load_dword v193, v3, s[6:7] offset:2048 nt
	s_add_u32 s6, s6, 0x1000
	s_addc_u32 s7, s7, 0
	global_load_dword v194, v3, s[6:7] nt
	global_load_dword v195, v3, s[6:7] offset:2048 nt
	s_add_u32 s6, s6, 0xd000
	s_addc_u32 s7, s7, 0
	global_load_dword v196, v3, s[6:7] nt
	global_load_dword v197, v3, s[6:7] offset:2048 nt
	s_add_u32 s6, s6, 0x1000
	s_addc_u32 s7, s7, 0
	global_load_dword v198, v3, s[6:7] nt
	global_load_dword v199, v3, s[6:7] offset:2048 nt
	s_add_u32 s6, s6, 0x1000
	s_addc_u32 s7, s7, 0
	global_load_dword v200, v3, s[6:7] nt
	global_load_dword v201, v3, s[6:7] offset:2048 nt
	s_add_u32 s6, s6, 0x1000
	s_addc_u32 s7, s7, 0
	global_load_dword v202, v3, s[6:7] nt
	global_load_dword v203, v3, s[6:7] offset:2048 nt
	s_add_u32 s6, s6, 0xd000
	s_addc_u32 s7, s7, 0
	global_load_dword v204, v3, s[6:7] nt
	global_load_dword v205, v3, s[6:7] offset:2048 nt
	s_add_u32 s6, s6, 0x1000
	s_addc_u32 s7, s7, 0
	global_load_dword v206, v3, s[6:7] nt
	global_load_dword v207, v3, s[6:7] offset:2048 nt
	s_add_u32 s6, s6, 0x1000
	s_addc_u32 s7, s7, 0
	global_load_dword v208, v3, s[6:7] nt
	global_load_dword v209, v3, s[6:7] offset:2048 nt
	s_add_u32 s6, s6, 0x1000
	s_addc_u32 s7, s7, 0
	global_load_dword v210, v3, s[6:7] nt
	global_load_dword v211, v3, s[6:7] offset:2048 nt
	v_mul_u32_u24_e32 v4, 0x2080, v0
	v_lshrrev_b32_e32 v5, 1, v2
	v_lshl_add_u32 v4, v5, 5, v4
	v_and_b32_e32 v5, 1, v2
	v_lshl_add_u32 v4, v5, 3, v4
	s_mul_i32 s8, s3, 0x2080
	s_and_b32 s9, s22, 127
	s_lshl_b32 s9, s9, 6
	s_add_u32 s8, s8, s9
	s_add_u32 s8, s44, s8
	s_addc_u32 s9, s45, 0
	s_waitcnt vmcnt(56)
; DI unsigned pk2(float lo, float hi) { unsigned r; asm("v_cvt_pk_bf16_f32 %0, %1, %2" : "=v"(r) : "v"(lo), "v"(hi)); return r; }
; DI void conv_cache_v(const P& p, int layer, int it) {
;     ...
;   bf16_t* dst = (bf16_t*)(p.ws + W_VTS) + ((size_t)(b * 8 + h) * 64 + d) * LS + (key0 & ~15) + ((key0 & 8) >> 1);
;   *(u32x2*)dst = u32x2{pk2(v[0], v[1]), pk2(v[2], v[3])};
;   *(u32x2*)(dst + 8) = u32x2{pk2(v[4], v[5]), pk2(v[6], v[7])};
; }
	v_cvt_pk_bf16_f32 v104, v104, v105
	v_cvt_pk_bf16_f32 v105, v106, v107
	v_cvt_pk_bf16_f32 v106, v108, v109
	v_cvt_pk_bf16_f32 v107, v110, v111
	global_store_dwordx2 v4, v[104:105], s[8:9]
	global_store_dwordx2 v4, v[106:107], s[8:9] offset:16
	s_add_u32 s8, s8, 64
	s_addc_u32 s9, s9, 0
	s_waitcnt vmcnt(50)
	v_cvt_pk_bf16_f32 v112, v112, v113
	v_cvt_pk_bf16_f32 v113, v114, v115
	v_cvt_pk_bf16_f32 v114, v116, v117
	v_cvt_pk_bf16_f32 v115, v118, v119
	global_store_dwordx2 v4, v[112:113], s[8:9]
	global_store_dwordx2 v4, v[114:115], s[8:9] offset:16
	s_add_u32 s8, s8, 64
	s_addc_u32 s9, s9, 0
	s_waitcnt vmcnt(44)
	v_cvt_pk_bf16_f32 v120, v120, v121
	v_cvt_pk_bf16_f32 v121, v122, v123
	v_cvt_pk_bf16_f32 v122, v124, v125
	v_cvt_pk_bf16_f32 v123, v126, v127
	global_store_dwordx2 v4, v[120:121], s[8:9]
	global_store_dwordx2 v4, v[122:123], s[8:9] offset:16
	s_add_u32 s8, s8, 64
	s_addc_u32 s9, s9, 0
	s_waitcnt vmcnt(38)
	v_cvt_pk_bf16_f32 v128, v128, v129
	v_cvt_pk_bf16_f32 v129, v130, v131
	v_cvt_pk_bf16_f32 v130, v132, v133
	v_cvt_pk_bf16_f32 v131, v134, v135
	global_store_dwordx2 v4, v[128:129], s[8:9]
	global_store_dwordx2 v4, v[130:131], s[8:9] offset:16
	s_add_u32 s8, s8, 64
	s_addc_u32 s9, s9, 0
	s_waitcnt vmcnt(32)
	v_cvt_pk_bf16_f32 v180, v180, v181
	v_cvt_pk_bf16_f32 v181, v182, v183
	v_cvt_pk_bf16_f32 v182, v184, v185
	v_cvt_pk_bf16_f32 v183, v186, v187
	global_store_dwordx2 v4, v[180:181], s[8:9]
	global_store_dwordx2 v4, v[182:183], s[8:9] offset:16
	s_add_u32 s8, s8, 64
	s_addc_u32 s9, s9, 0
	s_waitcnt vmcnt(26)
	v_cvt_pk_bf16_f32 v188, v188, v189
	v_cvt_pk_bf16_f32 v189, v190, v191
	v_cvt_pk_bf16_f32 v190, v192, v193
	v_cvt_pk_bf16_f32 v191, v194, v195
	global_store_dwordx2 v4, v[188:189], s[8:9]
	global_store_dwordx2 v4, v[190:191], s[8:9] offset:16
	s_add_u32 s8, s8, 64
	s_addc_u32 s9, s9, 0
	s_waitcnt vmcnt(20)
	v_cvt_pk_bf16_f32 v196, v196, v197
	v_cvt_pk_bf16_f32 v197, v198, v199
	v_cvt_pk_bf16_f32 v198, v200, v201
	v_cvt_pk_bf16_f32 v199, v202, v203
	global_store_dwordx2 v4, v[196:197], s[8:9]
	global_store_dwordx2 v4, v[198:199], s[8:9] offset:16
	s_add_u32 s8, s8, 64
	s_addc_u32 s9, s9, 0
	s_waitcnt vmcnt(14)
	v_cvt_pk_bf16_f32 v204, v204, v205
	v_cvt_pk_bf16_f32 v205, v206, v207
	v_cvt_pk_bf16_f32 v206, v208, v209
	v_cvt_pk_bf16_f32 v207, v210, v211
	global_store_dwordx2 v4, v[204:205], s[8:9]
	global_store_dwordx2 v4, v[206:207], s[8:9] offset:16
	s_movk_i32 s9, 0x1000

; DI int tidx() { int t = __builtin_amdgcn_workitem_id_x(); asm volatile("" : "+v"(t)); return t; }
; DI unsigned pk2(float lo, float hi) { unsigned r; asm("v_cvt_pk_bf16_f32 %0, %1, %2" : "=v"(r) : "v"(lo), "v"(hi)); return r; }
; DI void conv_cache_k(const P& p, int layer, int it) {
;   const size_t e0 = ((size_t)it * 256 + tidx()) * 8;
;   const int b = (int)(e0 / (4096ull * 512)), rem = (int)(e0 % (4096ull * 512));
;   const float* s = p.cache_k + (size_t)layer * 8 * 4096 * 512 + e0;
;   const f32x4 v0 = __builtin_nontemporal_load((const f32x4*)s), v1 = __builtin_nontemporal_load((const f32x4*)(s + 4));
;   bf16_t* d = (bf16_t*)(p.ws + W_KS) + (size_t)b * LS * 512 + rem;
;   *(u32x4*)d = u32x4{pk2(v0.x, v0.y), pk2(v0.z, v0.w), pk2(v1.x, v1.y), pk2(v1.z, v1.w)};
; }
; PHASE_FN void phaseB(const P& p, int layer, char* lds) {
;     ...
;       for (int k = 0; k < 8; ++k) conv_cache_k(p, layer, (mi - NPG) * 8 + k);
.LBB0_398:
	v_lshlrev_b32_e32 v0, 5, v158
	global_load_dwordx4 v[104:107], v0, s[4:5] nt
	global_load_dwordx4 v[108:111], v0, s[4:5] offset:16 nt
	s_add_u32 s4, s4, 0x2000
	s_addc_u32 s5, s5, 0
	global_load_dwordx4 v[112:115], v0, s[4:5] nt
	global_load_dwordx4 v[116:119], v0, s[4:5] offset:16 nt
	s_add_u32 s4, s4, 0x2000
	s_addc_u32 s5, s5, 0
	global_load_dwordx4 v[120:123], v0, s[4:5] nt
	global_load_dwordx4 v[124:127], v0, s[4:5] offset:16 nt
	s_add_u32 s4, s4, 0x2000
	s_addc_u32 s5, s5, 0
	global_load_dwordx4 v[128:131], v0, s[4:5] nt
	global_load_dwordx4 v[132:135], v0, s[4:5] offset:16 nt
	s_add_u32 s4, s4, 0x2000
	s_addc_u32 s5, s5, 0
	global_load_dwordx4 v[180:183], v0, s[4:5] nt
	global_load_dwordx4 v[184:187], v0, s[4:5] offset:16 nt
	s_add_u32 s4, s4, 0x2000
	s_addc_u32 s5, s5, 0
	global_load_dwordx4 v[188:191], v0, s[4:5] nt
	global_load_dwordx4 v[192:195], v0, s[4:5] offset:16 nt
	s_add_u32 s4, s4, 0x2000
	s_addc_u32 s5, s5, 0
	global_load_dwordx4 v[196:199], v0, s[4:5] nt
	global_load_dwordx4 v[200:203], v0, s[4:5] offset:16 nt
	s_add_u32 s4, s4, 0x2000
	s_addc_u32 s5, s5, 0
	global_load_dwordx4 v[204:207], v0, s[4:5] nt
	global_load_dwordx4 v[208:211], v0, s[4:5] offset:16 nt
	s_lshr_b64 s[6:7], s[0:1], 21
	s_mul_i32 s6, s6, 0x410000
	s_and_b32 s7, s0, 0x1fffff
	s_lshl_b32 s7, s7, 1
	s_add_u32 s6, s6, s7
	s_add_u32 s2, s48, s6
	s_addc_u32 s3, s49, 0
	v_lshlrev_b32_e32 v2, 4, v158
	s_waitcnt vmcnt(14)
	v_cvt_pk_bf16_f32 v104, v104, v105
	v_cvt_pk_bf16_f32 v105, v106, v107
	v_cvt_pk_bf16_f32 v106, v108, v109
	v_cvt_pk_bf16_f32 v107, v110, v111
	global_store_dwordx4 v2, v[104:107], s[2:3]
	s_add_u32 s2, s2, 0x1000
	s_addc_u32 s3, s3, 0
	s_waitcnt vmcnt(13)
	v_cvt_pk_bf16_f32 v112, v112, v113
	v_cvt_pk_bf16_f32 v113, v114, v115
	v_cvt_pk_bf16_f32 v114, v116, v117
	v_cvt_pk_bf16_f32 v115, v118, v119
	global_store_dwordx4 v2, v[112:115], s[2:3]
	s_add_u32 s2, s2, 0x1000
	s_addc_u32 s3, s3, 0
	s_waitcnt vmcnt(12)
	v_cvt_pk_bf16_f32 v120, v120, v121
	v_cvt_pk_bf16_f32 v121, v122, v123
	v_cvt_pk_bf16_f32 v122, v124, v125
	v_cvt_pk_bf16_f32 v123, v126, v127
	global_store_dwordx4 v2, v[120:123], s[2:3]
	s_add_u32 s2, s2, 0x1000
	s_addc_u32 s3, s3, 0
	s_waitcnt vmcnt(11)
	v_cvt_pk_bf16_f32 v128, v128, v129
	v_cvt_pk_bf16_f32 v129, v130, v131
	v_cvt_pk_bf16_f32 v130, v132, v133
	v_cvt_pk_bf16_f32 v131, v134, v135
	global_store_dwordx4 v2, v[128:131], s[2:3]
	s_add_u32 s2, s2, 0x1000
	s_addc_u32 s3, s3, 0
	s_waitcnt vmcnt(10)
	v_cvt_pk_bf16_f32 v180, v180, v181
	v_cvt_pk_bf16_f32 v181, v182, v183
	v_cvt_pk_bf16_f32 v182, v184, v185
	v_cvt_pk_bf16_f32 v183, v186, v187
	global_store_dwordx4 v2, v[180:183], s[2:3]
	s_add_u32 s2, s2, 0x1000
	s_addc_u32 s3, s3, 0
	s_waitcnt vmcnt(9)
	v_cvt_pk_bf16_f32 v188, v188, v189
	v_cvt_pk_bf16_f32 v189, v190, v191
	v_cvt_pk_bf16_f32 v190, v192, v193
	v_cvt_pk_bf16_f32 v191, v194, v195
	global_store_dwordx4 v2, v[188:191], s[2:3]
	s_add_u32 s2, s2, 0x1000
	s_addc_u32 s3, s3, 0
	s_waitcnt vmcnt(8)
	v_cvt_pk_bf16_f32 v196, v196, v197
	v_cvt_pk_bf16_f32 v197, v198, v199
	v_cvt_pk_bf16_f32 v198, v200, v201
	v_cvt_pk_bf16_f32 v199, v202, v203
	global_store_dwordx4 v2, v[196:199], s[2:3]
	s_add_u32 s2, s2, 0x1000
	s_addc_u32 s3, s3, 0
	s_waitcnt vmcnt(7)
	v_cvt_pk_bf16_f32 v204, v204, v205
	v_cvt_pk_bf16_f32 v205, v206, v207
	v_cvt_pk_bf16_f32 v206, v208, v209
	v_cvt_pk_bf16_f32 v207, v210, v211
	global_store_dwordx4 v2, v[204:207], s[2:3]

; DI int tidx() { int t = __builtin_amdgcn_workitem_id_x(); asm volatile("" : "+v"(t)); return t; }
; DI unsigned pk2(float lo, float hi) { unsigned r; asm("v_cvt_pk_bf16_f32 %0, %1, %2" : "=v"(r) : "v"(lo), "v"(hi)); return r; }
; DI void xconv_item(const P& p, int it) {
;   const int lane = tidx() & 63, wave = __builtin_amdgcn_readfirstlane(tidx() >> 6);
;   const int row = it * 4 + wave;
;   const float* x = (row < NTP) ? (p.x_p + (size_t)row * DM) : (p.x_s + (size_t)(row - NTP) * DM);
;   bf16_t* xb = (bf16_t*)(p.ws + W_XB) + (size_t)row * DM;
;   float ss = 0.f;
; #pragma unroll
;   for (int j = 0; j < 4; ++j) {
;     const f32x4 v = *(const f32x4*)(x + j * 256 + lane * 4);
;     ss += v.x * v.x + v.y * v.y + v.z * v.z + v.w * v.w;
;     *(u32x2*)(xb + j * 256 + lane * 4) = u32x2{pk2(v.x, v.y), pk2(v.z, v.w)};
;   }
;   ss = wave_sum(ss);
;   if (lane < 16) ((float*)(p.ws + W_SS))[(size_t)row * 16 + lane] = (lane == 0) ? ss : 0.f;
; }
.LBB0_2047:
	v_and_b32_e32 v0, 63, v0
	v_lshlrev_b32_e32 v6, 4, v0
	global_load_dwordx4 v[104:107], v6, s[2:3]
	global_load_dwordx4 v[108:111], v6, s[2:3] offset:1024
	global_load_dwordx4 v[112:115], v6, s[2:3] offset:2048
	global_load_dwordx4 v[2:5], v6, s[2:3] offset:3072
	s_lshl_b64 s[4:5], s[0:1], 11
	s_add_u32 s4, s74, s4
	s_addc_u32 s5, s75, s5
	v_lshlrev_b32_e32 v7, 3, v0
	s_waitcnt vmcnt(3)
	v_mul_f32_e32 v8, v105, v105
	v_fmac_f32_e32 v8, v104, v104
	v_fmac_f32_e32 v8, v106, v106
	v_fmac_f32_e32 v8, v107, v107
	v_cvt_pk_bf16_f32 v104, v104, v105
	v_cvt_pk_bf16_f32 v105, v106, v107
	global_store_dwordx2 v7, v[104:105], s[4:5]
	s_waitcnt vmcnt(3)
	v_mul_f32_e32 v9, v109, v109
	v_fmac_f32_e32 v9, v108, v108
	v_fmac_f32_e32 v9, v110, v110
	v_fmac_f32_e32 v9, v111, v111
	v_cvt_pk_bf16_f32 v108, v108, v109
	v_cvt_pk_bf16_f32 v109, v110, v111
	global_store_dwordx2 v7, v[108:109], s[4:5] offset:512
	v_add_f32_e32 v8, v8, v9
	s_waitcnt vmcnt(3)
	v_mul_f32_e32 v9, v113, v113
	v_fmac_f32_e32 v9, v112, v112
	v_fmac_f32_e32 v9, v114, v114
	v_fmac_f32_e32 v9, v115, v115
	v_cvt_pk_bf16_f32 v112, v112, v113
	v_cvt_pk_bf16_f32 v113, v114, v115
	global_store_dwordx2 v7, v[112:113], s[4:5] offset:1024
	v_add_f32_e32 v8, v8, v9
	s_waitcnt vmcnt(3)
	v_mul_f32_e32 v6, v3, v3
	v_fmac_f32_e32 v6, v2, v2
	v_cvt_pk_bf16_f32 v2, v2, v3
	v_cvt_pk_bf16_f32 v3, v4, v5
	global_store_dwordx2 v7, v[2:3], s[4:5] offset:1536
	v_and_b32_e32 v2, 64, v170
	v_add_u32_e32 v3, 64, v2
	v_xor_b32_e32 v2, 1, v170
	v_fmac_f32_e32 v6, v4, v4
	v_cmp_lt_i32_e32 vcc, v2, v3
	v_fmac_f32_e32 v6, v5, v5
	v_add_f32_e32 v6, v8, v6
	v_cndmask_b32_e32 v2, v170, v2, vcc
	v_lshlrev_b32_e32 v2, 2, v2
	ds_bpermute_b32 v2, v2, v6
	v_xor_b32_e32 v4, 2, v170
	v_cmp_lt_i32_e32 vcc, v4, v3
	s_waitcnt lgkmcnt(0)
	v_add_f32_e32 v2, v6, v2
	v_cndmask_b32_e32 v4, v170, v4, vcc
	v_lshlrev_b32_e32 v4, 2, v4
	ds_bpermute_b32 v4, v4, v2
	s_waitcnt lgkmcnt(0)
	v_add_f32_e32 v2, v2, v4
	v_xor_b32_e32 v4, 4, v170
	v_cmp_lt_i32_e32 vcc, v4, v3
	s_nop 1
	v_cndmask_b32_e32 v4, v170, v4, vcc
	v_lshlrev_b32_e32 v4, 2, v4
	ds_bpermute_b32 v4, v4, v2
	s_waitcnt lgkmcnt(0)
	v_add_f32_e32 v2, v2, v4
	v_xor_b32_e32 v4, 8, v170
	v_cmp_lt_i32_e32 vcc, v4, v3
	s_nop 1
	v_cndmask_b32_e32 v4, v170, v4, vcc
	v_lshlrev_b32_e32 v4, 2, v4
	ds_bpermute_b32 v4, v4, v2
	s_waitcnt lgkmcnt(0)
	v_add_f32_e32 v2, v2, v4
	v_xor_b32_e32 v4, 16, v170
	v_cmp_lt_i32_e32 vcc, v4, v3
	s_nop 1
	v_cndmask_b32_e32 v4, v170, v4, vcc
	v_lshlrev_b32_e32 v4, 2, v4
	ds_bpermute_b32 v4, v4, v2
	s_waitcnt lgkmcnt(0)
	v_add_f32_e32 v2, v2, v4
	v_xor_b32_e32 v4, 32, v170
	v_cmp_lt_i32_e32 vcc, v4, v3
	s_nop 1
	v_cndmask_b32_e32 v3, v170, v4, vcc
	v_lshlrev_b32_e32 v3, 2, v3
	ds_bpermute_b32 v3, v3, v2
	v_cmp_gt_u32_e32 vcc, 16, v0
	s_and_saveexec_b64 s[2:3], vcc
	s_cbranch_execz .LBB0_2049
	s_lshl_b64 s[0:1], s[0:1], 6
	s_waitcnt lgkmcnt(0)
	v_add_f32_e32 v2, v2, v3
	v_cmp_eq_u32_e32 vcc, 0, v0
	s_add_u32 s0, s66, s0
	s_addc_u32 s1, s67, s1
	v_cndmask_b32_e32 v2, 0, v2, vcc
	v_lshlrev_b32_e32 v0, 2, v0
	global_store_dword v0, v2, s[0:1]
